# gate_fixup loop: the 12 loads of each 512-column step issued together (one wait) instead of four dependent waits
# speedup vs baseline: 1.0079x; 1.0079x over previous
.LBB0_797:
	s_cmp_gt_i32 s90, 31
	s_cselect_b64 s[22:23], -1, 0
	s_and_b64 s[0:1], s[0:1], s[22:23]
	s_andn2_b64 vcc, exec, s[0:1]
	s_cbranch_vccnz .LBB0_808
	s_movk_i32 s0, 0xb00
	v_cmp_gt_i32_e32 vcc, s0, v192
	s_and_saveexec_b64 s[0:1], vcc
	s_cbranch_execz .LBB0_807
	s_sub_i32 s22, s90, 32
	s_cmp_eq_u32 s55, 16
	s_mul_hi_u32 s26, s22, 0x10800
	s_mul_i32 s33, s22, 0x10800
	s_cselect_b32 s22, 0x8400, 0
	s_cselect_b32 s34, 0x2c00, 0
	s_add_u32 s22, s68, s22
	s_addc_u32 s23, s69, 0
	s_add_u32 s36, s70, s34
	s_addc_u32 s37, s71, 0
	s_and_b32 s34, s90, 3
	s_cmp_lg_u32 s34, 0
	s_cselect_b64 s[38:39], -1, 0
	s_lshl_b32 s35, s90, 8
	s_cmp_lg_u32 s34, 3
	s_cselect_b64 s[40:41], -1, 0
	s_add_u32 s60, s78, s33
	s_mul_i32 s42, s90, 0x160000
	s_addc_u32 s61, s79, s26
	v_readlane_b32 s44, v253, 8
	s_mul_hi_u32 s35, s35, 0x1600
	v_readlane_b32 s45, v253, 9
	s_add_u32 s34, s44, s42
	v_ashrrev_i32_e32 v193, 31, v192
	s_addc_u32 s35, s45, s35
	v_add_u32_e32 v8, 0xfffffe00, v192
	v_lshlrev_b64 v[0:1], 2, v[192:193]
	s_movk_i32 s42, 0x210
	v_lshl_add_u64 v[2:3], v[192:193], 1, s[34:35]
	s_mov_b64 s[62:63], 0
	s_add_u32 s100, s60, 0xfdfa800
	s_addc_u32 s101, s61, 0
	global_load_dword v4, v0, s[22:23]
	v_add_u32_e32 v6, 0x2c00, v0
	global_load_dword v9, v6, s[22:23]
	v_add_u32_e32 v6, 0x5800, v0
	global_load_dword v5, v6, s[22:23]
	global_load_dword v10, v0, s[36:37]
	s_and_b64 vcc, exec, s[38:39]
	s_cbranch_vccz .Lgf_h2l_0
	global_load_dword v12, v0, s[100:101]
	v_add_u32_e32 v6, 0x5800, v0
	global_load_dword v11, v6, s[100:101]
	v_add_u32_e32 v6, 0x8400, v0
	global_load_dword v13, v6, s[100:101]
	v_add_u32_e32 v6, 0xb000, v0
	global_load_dword v1, v6, s[100:101]
.Lgf_h2l_0:
	s_and_b64 vcc, exec, s[40:41]
	s_cbranch_vccz .Lgf_c_0
	v_add_u32_e32 v6, 0xdc00, v0
	global_load_dword v14, v6, s[100:101]
	v_add_u32_e32 v6, 0x10800, v0
	global_load_dword v7, v6, s[100:101]
	v_add_u32_e32 v6, 0x16000, v0
	global_load_dword v15, v6, s[100:101]
	v_add_u32_e32 v6, 0x13400, v0
	global_load_dword v8, v6, s[100:101]
.Lgf_c_0:
	s_waitcnt vmcnt(0)
	s_and_b64 vcc, exec, s[38:39]
	s_cbranch_vccz .Lgf_h2c_0
	v_pk_mul_f32 v[12:13], v[4:5], v[12:13]
	s_nop 0
	v_fma_f32 v11, v9, v11, v12
	v_add_f32_e32 v11, v11, v13
	v_add_f32_e32 v11, v10, v11
	v_mul_f32_e32 v12, v11, v11
	v_fmamk_f32 v12, v12, 0xbdd2d3e8, v216
	v_mul_f32_e32 v12, v11, v12
	v_exp_f32_e32 v12, v12
	s_nop 0
	v_add_f32_e32 v12, 1.0, v12
	v_rcp_f32_e32 v12, v12
	s_nop 0
	v_mul_f32_e32 v11, v11, v12
	v_mul_f32_e32 v11, v1, v11
	v_cvt_pk_bf16_f32 v11, v11, v179
	global_store_short v[2:3], v11, off
.Lgf_h2c_0:
	s_and_b64 vcc, exec, s[40:41]
	s_cbranch_vccz .Lgf_n_0
	v_pk_mul_f32 v[14:15], v[4:5], v[14:15]
	s_nop 0
	v_fma_f32 v7, v9, v7, v14
	v_add_f32_e32 v7, v7, v15
	v_add_f32_e32 v7, v10, v7
	v_mul_f32_e32 v14, v7, v7
	v_fmamk_f32 v14, v14, 0xbdd2d3e8, v216
	v_mul_f32_e32 v14, v7, v14
	v_exp_f32_e32 v14, v14
	s_nop 0
	v_add_f32_e32 v14, 1.0, v14
	v_rcp_f32_e32 v14, v14
	s_nop 0
	v_mul_f32_e32 v7, v7, v14
	v_mul_f32_e32 v7, v8, v7
	v_cvt_pk_bf16_f32 v7, v7, v179
	v_add_co_u32_e32 v4, vcc, 0x15e000, v2
	s_nop 1
	v_addc_co_u32_e32 v5, vcc, 0, v3, vcc
	global_store_short v[4:5], v7, off offset:2560
.Lgf_n_0:
	v_add_u32_e32 v0, 0x800, v0
	v_add_co_u32_e32 v2, vcc, 0x400, v2
	s_nop 1
	v_addc_co_u32_e32 v3, vcc, 0, v3, vcc
	global_load_dword v4, v0, s[22:23]
	v_add_u32_e32 v6, 0x2c00, v0
	global_load_dword v9, v6, s[22:23]
	v_add_u32_e32 v6, 0x5800, v0
	global_load_dword v5, v6, s[22:23]
	global_load_dword v10, v0, s[36:37]
	s_and_b64 vcc, exec, s[38:39]
	s_cbranch_vccz .Lgf_h2l_1
	global_load_dword v12, v0, s[100:101]
	v_add_u32_e32 v6, 0x5800, v0
	global_load_dword v11, v6, s[100:101]
	v_add_u32_e32 v6, 0x8400, v0
	global_load_dword v13, v6, s[100:101]
	v_add_u32_e32 v6, 0xb000, v0
	global_load_dword v1, v6, s[100:101]

.Lgf_n_4:
	v_add_u32_e32 v0, 0x800, v0
	v_add_co_u32_e32 v2, vcc, 0x400, v2
	s_nop 1
	v_addc_co_u32_e32 v3, vcc, 0, v3, vcc
	s_mov_b64 s[34:35], exec
	v_cmp_gt_u32_e32 vcc, 0x100, v192
	s_nop 1
	s_and_b64 exec, exec, vcc
	s_cbranch_execz .Lgf_done
	global_load_dword v4, v0, s[22:23]
	v_add_u32_e32 v6, 0x2c00, v0
	global_load_dword v9, v6, s[22:23]
	v_add_u32_e32 v6, 0x5800, v0
	global_load_dword v5, v6, s[22:23]
	global_load_dword v10, v0, s[36:37]
	s_and_b64 vcc, exec, s[38:39]
	s_cbranch_vccz .Lgf_h2l_5
	global_load_dword v12, v0, s[100:101]
	v_add_u32_e32 v6, 0x5800, v0
	global_load_dword v11, v6, s[100:101]
	v_add_u32_e32 v6, 0x8400, v0
	global_load_dword v13, v6, s[100:101]
	v_add_u32_e32 v6, 0xb000, v0
	global_load_dword v1, v6, s[100:101]

.Lgf_n_5:
.Lgf_done:
	s_mov_b64 exec, s[34:35]

	.amdhsa_kernel _Z10fwd_kernel4Args
		.amdhsa_group_segment_fixed_size 0
		.amdhsa_private_segment_fixed_size 0
		.amdhsa_kernarg_size 456
		.amdhsa_user_sgpr_count 2
		.amdhsa_user_sgpr_dispatch_ptr 0
		.amdhsa_user_sgpr_queue_ptr 0
		.amdhsa_user_sgpr_kernarg_segment_ptr 1
		.amdhsa_user_sgpr_dispatch_id 0
		.amdhsa_user_sgpr_kernarg_preload_length 0
		.amdhsa_user_sgpr_kernarg_preload_offset 0
		.amdhsa_user_sgpr_private_segment_size 0
		.amdhsa_uses_dynamic_stack 0
		.amdhsa_enable_private_segment 0
		.amdhsa_system_sgpr_workgroup_id_x 1
		.amdhsa_system_sgpr_workgroup_id_y 0
		.amdhsa_system_sgpr_workgroup_id_z 0
		.amdhsa_system_sgpr_workgroup_info 0
		.amdhsa_system_vgpr_workitem_id 2
		.amdhsa_next_free_vgpr 256
		.amdhsa_next_free_sgpr 102
		.amdhsa_accum_offset 256
		.amdhsa_reserve_vcc 1
		.amdhsa_float_round_mode_32 0
		.amdhsa_float_round_mode_16_64 0
		.amdhsa_float_denorm_mode_32 3
		.amdhsa_float_denorm_mode_16_64 3
		.amdhsa_dx10_clamp 1
		.amdhsa_ieee_mode 1
		.amdhsa_fp16_overflow 0
		.amdhsa_tg_split 0
		.amdhsa_exception_fp_ieee_invalid_op 0
		.amdhsa_exception_fp_denorm_src 0
		.amdhsa_exception_fp_ieee_div_zero 0
		.amdhsa_exception_fp_ieee_overflow 0
		.amdhsa_exception_fp_ieee_underflow 0
		.amdhsa_exception_fp_ieee_inexact 0
		.amdhsa_exception_int_div_zero 0
	.end_amdhsa_kernel

amdhsa.kernels:
  - .agpr_count:     0
    .args:
      - .offset:         0
        .size:           200
        .value_kind:     by_value
      - .offset:         200
        .size:           4
        .value_kind:     hidden_block_count_x
      - .offset:         204
        .size:           4
        .value_kind:     hidden_block_count_y
      - .offset:         208
        .size:           4
        .value_kind:     hidden_block_count_z
      - .offset:         212
        .size:           2
        .value_kind:     hidden_group_size_x
      - .offset:         214
        .size:           2
        .value_kind:     hidden_group_size_y
      - .offset:         216
        .size:           2
        .value_kind:     hidden_group_size_z
      - .offset:         218
        .size:           2
        .value_kind:     hidden_remainder_x
      - .offset:         220
        .size:           2
        .value_kind:     hidden_remainder_y
      - .offset:         222
        .size:           2
        .value_kind:     hidden_remainder_z
      - .offset:         240
        .size:           8
        .value_kind:     hidden_global_offset_x
      - .offset:         248
        .size:           8
        .value_kind:     hidden_global_offset_y
      - .offset:         256
        .size:           8
        .value_kind:     hidden_global_offset_z
      - .offset:         264
        .size:           2
        .value_kind:     hidden_grid_dims
      - .offset:         288
        .size:           8
        .value_kind:     hidden_multigrid_sync_arg
      - .offset:         320
        .size:           4
        .value_kind:     hidden_dynamic_lds_size
    .group_segment_fixed_size: 0
    .kernarg_segment_align: 8
    .kernarg_segment_size: 456
    .language:       OpenCL C
    .language_version:
      - 2
      - 0
    .max_flat_workgroup_size: 512
    .name:           _Z10fwd_kernel4Args
    .private_segment_fixed_size: 0
    .sgpr_count:     108
    .sgpr_spill_count: 263
    .symbol:         _Z10fwd_kernel4Args.kd
    .uniform_work_group_size: 1
    .uses_dynamic_stack: false
    .vgpr_count:     256
    .vgpr_spill_count: 0
    .wavefront_size: 64
